# attention output epilogue: dwordx2 store pairs widened to dwordx4 via v_permlane16_swap (4 stores instead of 8 per lane)
# speedup vs baseline: 1.0063x; 1.0063x over previous
; DEV unsigned cvt_pk_bf16(float lo, float hi) { unsigned r; asm volatile("v_cvt_pk_bf16_f32 %0, %1, %2" : "=v"(r) : "v"(lo), "v"(hi)); return r; }
; DEV void attn_item(LAS unsigned char* lds, const bf16_t* P, const bf16_t* QB, const bf16_t* KV, const bf16_t* KC, const bf16_t* VC, const float* rel_bias, bf16_t* OB, int b, int g, int qt) {
;     ...
; #pragma unroll
;     for (int hh = 0; hh < 2; ++hh)
; #pragma unroll
;         for (int dt = 0; dt < 4; ++dt) { u32x2 w; w.x = cvt_pk_bf16(F[hh][dt][0], F[hh][dt][1]); w.y = cvt_pk_bf16(F[hh][dt][2], F[hh][dt][3]);
;             *(u32x2*)(OB + tok * 1024 + (g * 4 + hp * 2 + hh) * 64 + dt * 16 + g4 * 4) = w; }
.LBB0_157:
	v_lshl_add_u64 v[2:3], s[86:87], 0, v[96:97]
	v_lshlrev_b32_e32 v0, 1, v138
	v_lshl_add_u64 v[2:3], v[2:3], 0, v[0:1]
	v_lshlrev_b32_e32 v0, 1, v140
	v_lshl_add_u64 v[2:3], v[2:3], 0, v[0:1]
	v_and_b32_e32 v24, 16, v213
	v_lshrrev_b32_e32 v25, 1, v24
	v_add_u32_e32 v24, v24, v25
	v_add_co_u32_e32 v2, vcc, v2, v24
	s_nop 1
	v_addc_co_u32_e32 v3, vcc, 0, v3, vcc
	v_readlane_b32 s90, v254, 53
	v_readlane_b32 s92, v254, 55
	v_readlane_b32 s91, v254, 54
	v_readlane_b32 s93, v254, 56
	s_movk_i32 s94, 0x80
	v_readlane_b32 s95, v254, 58
	s_movk_i32 s96, 0x204
	s_movk_i32 s97, 0xb80
	v_cvt_pk_bf16_f32 v8, v134, v135
	v_cvt_pk_bf16_f32 v9, v130, v131
	v_cvt_pk_bf16_f32 v10, v132, v133
	v_cvt_pk_bf16_f32 v11, v128, v129
	v_cvt_pk_bf16_f32 v12, v124, v125
	v_cvt_pk_bf16_f32 v13, v120, v121
	v_cvt_pk_bf16_f32 v14, v122, v123
	v_cvt_pk_bf16_f32 v15, v118, v119
	v_cvt_pk_bf16_f32 v16, v116, v117
	v_cvt_pk_bf16_f32 v17, v114, v115
	v_cvt_pk_bf16_f32 v18, v112, v113
	v_cvt_pk_bf16_f32 v19, v110, v111
	v_cvt_pk_bf16_f32 v20, v108, v109
	v_cvt_pk_bf16_f32 v21, v104, v105
	v_cvt_pk_bf16_f32 v22, v106, v107
	v_cvt_pk_bf16_f32 v23, v102, v103
	s_nop 1
	v_permlane16_swap_b32_e32 v8, v10
	v_permlane16_swap_b32_e32 v9, v11
	v_permlane16_swap_b32_e32 v12, v14
	v_permlane16_swap_b32_e32 v13, v15
	v_permlane16_swap_b32_e32 v16, v18
	v_permlane16_swap_b32_e32 v17, v19
	v_permlane16_swap_b32_e32 v20, v22
	v_permlane16_swap_b32_e32 v21, v23
	global_store_dwordx4 v[2:3], v[8:11], off
	global_store_dwordx4 v[2:3], v[12:15], off offset:64
	global_store_dwordx4 v[2:3], v[16:19], off offset:128
	global_store_dwordx4 v[2:3], v[20:23], off offset:192
